# in-proj c_r loop: operand loads of a K slice issued together, two slices in flight (was one vmcnt(0) round trip per MFMA step)
# speedup vs baseline: 1.0101x; 1.0006x over previous
.LBB0_473:
	v_add_co_u32_e32 v26, vcc, 0x1e80000, v12
	s_nop 1
	v_addc_co_u32_e32 v27, vcc, 0, v13, vcc
	global_load_dwordx4 v[32:35], v[10:11], off offset:-256
	global_load_dwordx4 v[36:39], v[26:27], off offset:0
	global_load_dwordx4 v[40:43], v[10:11], off offset:-192
	global_load_dwordx4 v[44:47], v[26:27], off offset:64
	global_load_dwordx4 v[48:51], v[10:11], off offset:-128
	global_load_dwordx4 v[52:55], v[26:27], off offset:128
	global_load_dwordx4 v[56:59], v[10:11], off offset:-64
	global_load_dwordx4 v[60:63], v[26:27], off offset:192
	global_load_dwordx4 v[64:67], v[10:11], off offset:0
	global_load_dwordx4 v[68:71], v[26:27], off offset:256
	global_load_dwordx4 v[72:75], v[10:11], off offset:64
	global_load_dwordx4 v[76:79], v[26:27], off offset:320
	global_load_dwordx4 v[80:83], v[10:11], off offset:128
	global_load_dwordx4 v[84:87], v[26:27], off offset:384
	global_load_dwordx4 v[88:91], v[10:11], off offset:192
	global_load_dwordx4 v[92:95], v[26:27], off offset:448
	global_load_dwordx4 v[96:99], v[10:11], off offset:256
	global_load_dwordx4 v[100:103], v[26:27], off offset:512
	global_load_dwordx4 v[104:107], v[10:11], off offset:320
	global_load_dwordx4 v[108:111], v[26:27], off offset:576
	global_load_dwordx4 v[112:115], v[10:11], off offset:384
	global_load_dwordx4 v[116:119], v[26:27], off offset:640
	global_load_dwordx4 v[120:123], v[10:11], off offset:448
	global_load_dwordx4 v[124:127], v[26:27], off offset:704
	global_load_dwordx4 v[128:131], v[10:11], off offset:512
	global_load_dwordx4 v[132:135], v[26:27], off offset:768
	global_load_dwordx4 v[136:139], v[10:11], off offset:576
	global_load_dwordx4 v[144:147], v[26:27], off offset:832
	global_load_dwordx4 v[148:151], v[10:11], off offset:640
	global_load_dwordx4 v[152:155], v[26:27], off offset:896
	global_load_dwordx4 v[156:159], v[10:11], off offset:704
	global_load_dwordx4 v[160:163], v[26:27], off offset:960
	s_waitcnt vmcnt(30)
	v_mfma_f32_16x16x32_bf16 v[0:3], v[32:35], v[36:39], v[0:3]
	s_waitcnt vmcnt(28)
	v_mfma_f32_16x16x32_bf16 v[0:3], v[40:43], v[44:47], v[0:3]
	s_waitcnt vmcnt(26)
	v_mfma_f32_16x16x32_bf16 v[0:3], v[48:51], v[52:55], v[0:3]
	s_waitcnt vmcnt(24)
	v_mfma_f32_16x16x32_bf16 v[0:3], v[56:59], v[60:63], v[0:3]
	s_waitcnt vmcnt(22)
	v_mfma_f32_16x16x32_bf16 v[0:3], v[64:67], v[68:71], v[0:3]
	s_waitcnt vmcnt(20)
	v_mfma_f32_16x16x32_bf16 v[0:3], v[72:75], v[76:79], v[0:3]
	s_waitcnt vmcnt(18)
	v_mfma_f32_16x16x32_bf16 v[0:3], v[80:83], v[84:87], v[0:3]
	s_waitcnt vmcnt(16)
	v_mfma_f32_16x16x32_bf16 v[0:3], v[88:91], v[92:95], v[0:3]
	global_load_dwordx4 v[32:35], v[10:11], off offset:768
	global_load_dwordx4 v[36:39], v[26:27], off offset:1024
	global_load_dwordx4 v[40:43], v[10:11], off offset:832
	global_load_dwordx4 v[44:47], v[26:27], off offset:1088
	global_load_dwordx4 v[48:51], v[10:11], off offset:896
	global_load_dwordx4 v[52:55], v[26:27], off offset:1152
	global_load_dwordx4 v[56:59], v[10:11], off offset:960
	global_load_dwordx4 v[60:63], v[26:27], off offset:1216
	global_load_dwordx4 v[64:67], v[10:11], off offset:1024
	global_load_dwordx4 v[68:71], v[26:27], off offset:1280
	global_load_dwordx4 v[72:75], v[10:11], off offset:1088
	global_load_dwordx4 v[76:79], v[26:27], off offset:1344
	global_load_dwordx4 v[80:83], v[10:11], off offset:1152
	global_load_dwordx4 v[84:87], v[26:27], off offset:1408
	global_load_dwordx4 v[88:91], v[10:11], off offset:1216
	global_load_dwordx4 v[92:95], v[26:27], off offset:1472
	s_waitcnt vmcnt(30)
	v_mfma_f32_16x16x32_bf16 v[0:3], v[96:99], v[100:103], v[0:3]
	s_waitcnt vmcnt(28)
	v_mfma_f32_16x16x32_bf16 v[0:3], v[104:107], v[108:111], v[0:3]
	s_waitcnt vmcnt(26)
	v_mfma_f32_16x16x32_bf16 v[0:3], v[112:115], v[116:119], v[0:3]
	s_waitcnt vmcnt(24)
	v_mfma_f32_16x16x32_bf16 v[0:3], v[120:123], v[124:127], v[0:3]
	s_waitcnt vmcnt(22)
	v_mfma_f32_16x16x32_bf16 v[0:3], v[128:131], v[132:135], v[0:3]
	s_waitcnt vmcnt(20)
	v_mfma_f32_16x16x32_bf16 v[0:3], v[136:139], v[144:147], v[0:3]
	s_waitcnt vmcnt(18)
	v_mfma_f32_16x16x32_bf16 v[0:3], v[148:151], v[152:155], v[0:3]
	s_waitcnt vmcnt(16)
	v_mfma_f32_16x16x32_bf16 v[0:3], v[156:159], v[160:163], v[0:3]
	global_load_dwordx4 v[96:99], v[10:11], off offset:1280
	global_load_dwordx4 v[100:103], v[26:27], off offset:1536
	global_load_dwordx4 v[104:107], v[10:11], off offset:1344
	global_load_dwordx4 v[108:111], v[26:27], off offset:1600
	global_load_dwordx4 v[112:115], v[10:11], off offset:1408
	global_load_dwordx4 v[116:119], v[26:27], off offset:1664
	global_load_dwordx4 v[120:123], v[10:11], off offset:1472
	global_load_dwordx4 v[124:127], v[26:27], off offset:1728
	global_load_dwordx4 v[128:131], v[10:11], off offset:1536
	global_load_dwordx4 v[132:135], v[26:27], off offset:1792
	global_load_dwordx4 v[136:139], v[10:11], off offset:1600
	global_load_dwordx4 v[144:147], v[26:27], off offset:1856
	global_load_dwordx4 v[148:151], v[10:11], off offset:1664
	global_load_dwordx4 v[152:155], v[26:27], off offset:1920
	global_load_dwordx4 v[156:159], v[10:11], off offset:1728
	global_load_dwordx4 v[160:163], v[26:27], off offset:1984
	s_waitcnt vmcnt(30)
	v_mfma_f32_16x16x32_bf16 v[0:3], v[32:35], v[36:39], v[0:3]
	s_waitcnt vmcnt(28)
	v_mfma_f32_16x16x32_bf16 v[0:3], v[40:43], v[44:47], v[0:3]
	s_waitcnt vmcnt(26)
	v_mfma_f32_16x16x32_bf16 v[0:3], v[48:51], v[52:55], v[0:3]
	s_waitcnt vmcnt(24)
	v_mfma_f32_16x16x32_bf16 v[0:3], v[56:59], v[60:63], v[0:3]
	s_waitcnt vmcnt(22)
	v_mfma_f32_16x16x32_bf16 v[0:3], v[64:67], v[68:71], v[0:3]
	s_waitcnt vmcnt(20)
	v_mfma_f32_16x16x32_bf16 v[0:3], v[72:75], v[76:79], v[0:3]
	s_waitcnt vmcnt(18)
	v_mfma_f32_16x16x32_bf16 v[0:3], v[80:83], v[84:87], v[0:3]
	s_waitcnt vmcnt(16)
	v_mfma_f32_16x16x32_bf16 v[0:3], v[88:91], v[92:95], v[0:3]
	s_waitcnt vmcnt(14)
	v_mfma_f32_16x16x32_bf16 v[0:3], v[96:99], v[100:103], v[0:3]
	s_waitcnt vmcnt(12)
	v_mfma_f32_16x16x32_bf16 v[0:3], v[104:107], v[108:111], v[0:3]
	s_waitcnt vmcnt(10)
	v_mfma_f32_16x16x32_bf16 v[0:3], v[112:115], v[116:119], v[0:3]
	s_waitcnt vmcnt(8)
	v_mfma_f32_16x16x32_bf16 v[0:3], v[120:123], v[124:127], v[0:3]
	s_waitcnt vmcnt(6)
	v_mfma_f32_16x16x32_bf16 v[0:3], v[128:131], v[132:135], v[0:3]
	s_waitcnt vmcnt(4)
	v_mfma_f32_16x16x32_bf16 v[0:3], v[136:139], v[144:147], v[0:3]
	s_waitcnt vmcnt(2)
	v_mfma_f32_16x16x32_bf16 v[0:3], v[148:151], v[152:155], v[0:3]
	s_waitcnt vmcnt(0)
	v_mfma_f32_16x16x32_bf16 v[0:3], v[156:159], v[160:163], v[0:3]
	v_lshl_or_b32 v12, v14, 4, v15
	v_ashrrev_i32_e32 v13, 31, v12
	v_add_u32_e32 v14, s8, v14
	s_movk_i32 s6, 0x3ff
	v_lshlrev_b64 v[12:13], 6, v[12:13]
	v_cmp_lt_i32_e32 vcc, s6, v14
	v_lshl_add_u64 v[12:13], v[4:5], 0, v[12:13]
	s_or_b64 s[4:5], vcc, s[4:5]
	v_add_u32_e32 v8, s9, v8
	global_store_dwordx4 v[12:13], v[0:3], off sc1
	s_andn2_b64 exec, exec, s[4:5]
	s_cbranch_execnz .LBB0_472
